# P8 small-tile GEMM: exact counted vmcnt waits (two-chunk lookahead restored), on v25
# speedup vs baseline: 1.0034x; 1.0034x over previous
; #define LAS __attribute__((address_space(3)))
; #define SG_LOAD(kc, sg) do { _Pragma("unroll") for (int i_ = 0; i_ < 4; ++i_) { const int idx_ = tid + 512 * i_; \
;             ra[sg][i_] = *(const u32x4*)(A + (size_t)(row0 + (idx_ >> 5)) * ld + (kc) * 256 + (idx_ & 31) * 8); if (NC == 64 || i_ < 2) rb[sg][i_] = *(const u32x4*)(Bt + (size_t)(col0 + (idx_ >> 5)) * ld + (kc) * 256 + (idx_ & 31) * 8); } } while (0)
; template <int NC, class Epi>
; __device__ __forceinline__ void small_gemm_phase(LAS unsigned char* lds, const bf16_t* A, const bf16_t* Bt, int K, int ld, int ncolt  , const Epi& E, int first, int nblk, int bid, int tid) {
;     ...
;         SG_LOAD(0, 0); SG_LOAD(1, 1);
;         f32x4 acc0 = {0.f, 0.f, 0.f, 0.f}, acc1 = {0.f, 0.f, 0.f, 0.f};
;         const LAS unsigned char* apl = lds + (16 * mt + fr) * SG_STRIDE + 16 * fq;
;         const LAS unsigned char* bpl = lds + SG_BOFF + ((NC / 2) * nh + fr) * SG_STRIDE + 16 * fq;
; #pragma unroll 1
;         for (int kc = 0; kc < nch; kc += 2) { SG_STEP(kc, 0); SG_STEP(kc + 1, 1); }
.LBB0_1289:
	s_and_b32 s8, s13, 0x7fffffe0
	v_or_b32_e32 v52, s8, v95
	s_and_b32 s8, s18, 0x1c0
	v_lshlrev_b64 v[48:49], 13, v[52:53]
	v_add_lshl_u32 v52, v116, s8, 13
	v_lshl_add_u64 v[62:63], s[58:59], 0, v[52:53]
	v_add_lshl_u32 v52, v117, s8, 13
	v_lshl_add_u64 v[64:65], s[58:59], 0, v[52:53]
	v_add_lshl_u32 v52, v118, s8, 13
	v_lshl_add_u64 v[66:67], s[58:59], 0, v[52:53]
	v_add_lshl_u32 v52, v119, s8, 13
	s_lshl_b32 s8, s21, 6
	s_and_b32 s23, s8, 0x1c0
	s_bitset1_b32 s23, 14
	s_lshl_b32 s8, s21, 2
	v_or_b32_e32 v0, s23, v95
	v_lshl_add_u64 v[68:69], s[58:59], 0, v[52:53]
	s_and_b32 s22, s8, 0x7fffffe0
	v_lshlrev_b32_e32 v52, 13, v0
	v_lshl_add_u64 v[50:51], v[54:55], 0, v[52:53]
	v_or_b32_e32 v52, s22, v95
	v_lshlrev_b64 v[0:1], 13, v[52:53]
	v_lshl_add_u64 v[70:71], v[56:57], 0, v[0:1]
	v_or_b32_e32 v0, s23, v96
	v_lshlrev_b32_e32 v52, 13, v0
	v_lshl_add_u64 v[72:73], v[54:55], 0, v[52:53]
	v_add_u32_e32 v52, s22, v96
	v_lshlrev_b64 v[0:1], 13, v[52:53]
	v_lshl_add_u64 v[74:75], v[56:57], 0, v[0:1]
	v_or_b32_e32 v0, s23, v97
	v_lshlrev_b32_e32 v52, 13, v0
	v_lshl_add_u64 v[76:77], v[54:55], 0, v[52:53]
	v_add_lshl_u32 v52, s23, v98, 13
	v_lshl_add_u64 v[78:79], v[54:55], 0, v[52:53]
	global_load_dwordx4 v[0:3], v[50:51], off
	global_load_dwordx4 v[8:11], v[70:71], off
	global_load_dwordx4 v[16:19], v[72:73], off
	global_load_dwordx4 v[24:27], v[74:75], off
	global_load_dwordx4 v[32:35], v[76:77], off
	global_load_dwordx4 v[40:43], v[78:79], off
	global_load_dwordx4 v[4:7], v[50:51], off offset:512
	global_load_dwordx4 v[12:15], v[70:71], off offset:512
	global_load_dwordx4 v[20:23], v[72:73], off offset:512
	global_load_dwordx4 v[28:31], v[74:75], off offset:512
	global_load_dwordx4 v[36:39], v[76:77], off offset:512
	global_load_dwordx4 v[44:47], v[78:79], off offset:512
	s_bfe_u32 s8, s13, 0x1a0005
	s_lshl_b64 s[16:17], s[8:9], 18
	v_lshl_add_u64 v[70:71], v[60:61], 0, s[16:17]
	v_lshl_add_u64 v[72:73], s[58:59], 0, v[48:49]
	s_mov_b32 s8, 0
	v_mov_b32_e32 v48, 0
	v_mov_b32_e32 v49, v53
	v_mov_b32_e32 v50, v53
	v_mov_b32_e32 v51, v53
	s_branch .LBB0_1291

; #define LAS __attribute__((address_space(3)))
; #define SG_LOAD(kc, sg) do { _Pragma("unroll") for (int i_ = 0; i_ < 4; ++i_) { const int idx_ = tid + 512 * i_; \
;             ra[sg][i_] = *(const u32x4*)(A + (size_t)(row0 + (idx_ >> 5)) * ld + (kc) * 256 + (idx_ & 31) * 8); if (NC == 64 || i_ < 2) rb[sg][i_] = *(const u32x4*)(Bt + (size_t)(col0 + (idx_ >> 5)) * ld + (kc) * 256 + (idx_ & 31) * 8); } } while (0)
; template <int NC, class Epi>
; __device__ __forceinline__ void small_gemm_phase(LAS unsigned char* lds, const bf16_t* A, const bf16_t* Bt, int K, int ld, int ncolt  , const Epi& E, int first, int nblk, int bid, int tid) {
;     ...
;         SG_LOAD(0, 0); SG_LOAD(1, 1);
;         f32x4 acc0 = {0.f, 0.f, 0.f, 0.f}, acc1 = {0.f, 0.f, 0.f, 0.f};
;         const LAS unsigned char* apl = lds + (16 * mt + fr) * SG_STRIDE + 16 * fq;
;         const LAS unsigned char* bpl = lds + SG_BOFF + ((NC / 2) * nh + fr) * SG_STRIDE + 16 * fq;
; #pragma unroll 1
;         for (int kc = 0; kc < nch; kc += 2) { SG_STEP(kc, 0); SG_STEP(kc + 1, 1); }
.LBB0_1291:
	v_add_u32_e32 v52, v89, v99
	v_add_u32_e32 v74, v89, v100
	s_cmp_gt_u32 s8, 13
	s_waitcnt vmcnt(11)
	ds_write_b128 v52, v[0:3]
	s_waitcnt vmcnt(10)
	ds_write_b128 v52, v[8:11] offset:33792
	s_waitcnt vmcnt(9)
	ds_write_b128 v74, v[16:19]
	s_waitcnt vmcnt(8)
	ds_write_b128 v74, v[24:27] offset:33792
	s_waitcnt vmcnt(7)
	ds_write_b128 v52, v[32:35] offset:16896
	v_add_u32_e32 v52, v89, v101
	s_cselect_b64 s[16:17], -1, 0
	s_cmp_lt_u32 s8, 14
	v_lshl_add_u64 v[84:85], v[68:69], 0, v[58:59]
	v_lshl_add_u64 v[82:83], v[72:73], 0, v[58:59]
	v_lshl_add_u64 v[80:81], v[66:67], 0, v[58:59]
	v_lshl_add_u64 v[78:79], v[70:71], 0, v[58:59]
	v_lshl_add_u64 v[76:77], v[64:65], 0, v[58:59]
	v_lshl_add_u64 v[74:75], v[62:63], 0, v[58:59]
	s_waitcnt vmcnt(6)
	ds_write_b128 v52, v[40:43]
	s_cbranch_scc0 .Lsgw_p8_last
	v_add_co_u32_e32 v0, vcc, 0x2c00000, v84
	s_nop 1
	v_addc_co_u32_e32 v1, vcc, 0, v85, vcc
	v_add_co_u32_e32 v8, vcc, 0x1700000, v82
	global_load_dwordx4 v[0:3], v[0:1], off offset:1024
	s_nop 0
	v_addc_co_u32_e32 v9, vcc, 0, v83, vcc
	v_add_co_u32_e32 v16, vcc, 0x2c00000, v80
	global_load_dwordx4 v[8:11], v[8:9], off offset:1024
	s_nop 0
	v_addc_co_u32_e32 v17, vcc, 0, v81, vcc
	v_add_co_u32_e32 v24, vcc, 0x1700000, v78
	global_load_dwordx4 v[16:19], v[16:17], off offset:1024
	s_nop 0
	v_addc_co_u32_e32 v25, vcc, 0, v79, vcc
	v_add_co_u32_e32 v32, vcc, 0x2c00000, v76
	global_load_dwordx4 v[24:27], v[24:25], off offset:1024
	s_nop 0
	v_addc_co_u32_e32 v33, vcc, 0, v77, vcc
	v_add_co_u32_e32 v40, vcc, 0x2c00000, v74
	global_load_dwordx4 v[32:35], v[32:33], off offset:1024
	s_nop 0
	v_addc_co_u32_e32 v41, vcc, 0, v75, vcc
	global_load_dwordx4 v[40:43], v[40:41], off offset:1024
.LBB0_1293:
	s_waitcnt lgkmcnt(0)
	s_barrier
	ds_read_b128 v[120:123], v88 offset:33792
	ds_read_b128 v[124:127], v88 offset:33856
	ds_read_b128 v[128:131], v87
	ds_read_b128 v[132:135], v87 offset:64
	ds_read_b128 v[136:139], v88 offset:33920
	s_waitcnt lgkmcnt(2)
	v_mfma_f32_16x16x32_bf16 v[48:51], v[120:123], v[128:131], v[48:51]
	ds_read_b128 v[120:123], v87 offset:128
	ds_read_b128 v[128:131], v87 offset:192
	ds_read_b128 v[140:143], v88 offset:33984
	v_add_u32_e32 v52, v90, v99
	s_cmp_gt_u32 s8, 12
	s_waitcnt lgkmcnt(4)
	v_mfma_f32_16x16x32_bf16 v[48:51], v[124:127], v[132:135], v[48:51]
	ds_read_b128 v[124:127], v87 offset:256
	ds_read_b128 v[132:135], v87 offset:320
	ds_read_b128 v[144:147], v88 offset:34048
	ds_read_b128 v[148:151], v88 offset:34112
	s_waitcnt lgkmcnt(6)
	v_mfma_f32_16x16x32_bf16 v[48:51], v[136:139], v[120:123], v[48:51]
	ds_read_b128 v[120:123], v87 offset:384
	ds_read_b128 v[136:139], v87 offset:448
	ds_read_b128 v[152:155], v88 offset:34176
	ds_read_b128 v[156:159], v88 offset:34240
	s_waitcnt vmcnt(11)
	ds_write_b128 v52, v[4:7]
	s_waitcnt lgkmcnt(9)
	v_mfma_f32_16x16x32_bf16 v[48:51], v[140:143], v[128:131], v[48:51]
	v_add_u32_e32 v128, v91, v99
	s_waitcnt vmcnt(10)
	ds_write_b128 v128, v[12:15]
	s_waitcnt lgkmcnt(7)
	v_mfma_f32_16x16x32_bf16 v[48:51], v[144:147], v[124:127], v[48:51]
	v_add_u32_e32 v124, v90, v100
	s_waitcnt vmcnt(9)
	ds_write_b128 v124, v[20:23]
	v_add_u32_e32 v124, v91, v100
	s_waitcnt lgkmcnt(7)
	v_mfma_f32_16x16x32_bf16 v[48:51], v[148:151], v[132:135], v[48:51]
	s_waitcnt vmcnt(8)
	ds_write_b128 v124, v[28:31]
	s_waitcnt vmcnt(7)
	ds_write_b128 v52, v[36:39] offset:16896
	v_add_u32_e32 v52, v90, v101
	s_waitcnt vmcnt(6)
	ds_write_b128 v52, v[44:47]
	s_waitcnt lgkmcnt(7)
	v_mfma_f32_16x16x32_bf16 v[48:51], v[152:155], v[120:123], v[48:51]
	s_waitcnt lgkmcnt(6)
	v_mfma_f32_16x16x32_bf16 v[48:51], v[156:159], v[136:139], v[48:51]
	s_cbranch_scc1 .LBB0_1290
	v_add_co_u32_e32 v4, vcc, 0x2c00000, v84
	s_nop 1
	v_addc_co_u32_e32 v5, vcc, 0, v85, vcc
	v_add_co_u32_e32 v12, vcc, 0x1700000, v82
	global_load_dwordx4 v[4:7], v[4:5], off offset:1536
	s_nop 0
	v_addc_co_u32_e32 v13, vcc, 0, v83, vcc
	v_add_co_u32_e32 v20, vcc, 0x2c00000, v80
	global_load_dwordx4 v[12:15], v[12:13], off offset:1536
	s_nop 0
	v_addc_co_u32_e32 v21, vcc, 0, v81, vcc
	v_add_co_u32_e32 v28, vcc, 0x1700000, v78
	global_load_dwordx4 v[20:23], v[20:21], off offset:1536
	s_nop 0
	v_addc_co_u32_e32 v29, vcc, 0, v79, vcc
	v_add_co_u32_e32 v36, vcc, 0x2c00000, v76
	global_load_dwordx4 v[28:31], v[28:29], off offset:1536
	s_nop 0
	v_addc_co_u32_e32 v37, vcc, 0, v77, vcc
	v_add_co_u32_e32 v44, vcc, 0x2c00000, v74
	global_load_dwordx4 v[36:39], v[36:37], off offset:1536
	s_nop 0
	v_addc_co_u32_e32 v45, vcc, 0, v75, vcc
	global_load_dwordx4 v[44:47], v[44:45], off offset:1536
	s_branch .LBB0_1290
.Lsgw_p8_last:
	s_waitcnt vmcnt(0)
	s_branch .LBB0_1293
